# up GEMM: per-phase LDS rstd table (same summation tree) replaces per-tile ss loads + cross-lane reduction + rsqrt in EpiUp (101 instrs and a vmcnt(0) drain removed per tile)
# speedup vs baseline: 1.0050x; 1.0050x over previous
.LBB0_381:
	v_readlane_b32 s4, v254, 8
	v_readlane_b32 s5, v254, 9
	s_andn2_b64 vcc, exec, s[4:5]
	v_readfirstlane_b32 s28, v248
	s_cbranch_vccnz .LBB0_412
	s_waitcnt vmcnt(0) lgkmcnt(0)
	s_lshr_b32 s4, s28, 8
	v_and_b32_e32 v2, 0xff, v248
	v_lshlrev_b32_e32 v2, 2, v2
	s_add_i32 s5, s4, 0
	s_lshl_b32 s6, s5, 8
	s_add_i32 s6, s6, s2
	s_and_b32 s7, s6, 7
	s_mul_i32 s7, s7, 0x160
	s_lshr_b32 s20, s6, 3
	s_add_i32 s7, s7, s20
	s_lshr_b32 s20, s7, 3
	s_mul_i32 s20, s20, 0x1746
	s_lshr_b32 s20, s20, 16
	s_mul_i32 s21, s20, 0x58
	s_sub_i32 s21, s7, s21
	s_and_b32 s21, s21, 3
	s_lshl_b32 s20, s20, 2
	s_add_i32 s20, s20, s21
	s_lshl_b32 s20, s20, 10
	v_add_u32_e32 v3, s20, v2
	global_load_dword v4, v3, s[14:15]
	v_add_u32_e32 v3, 0x20000, v3
	global_load_dword v5, v3, s[14:15]
	v_add_u32_e32 v3, 0x20000, v3
	global_load_dword v6, v3, s[14:15]
	v_add_u32_e32 v3, 0x20000, v3
	global_load_dword v7, v3, s[14:15]
	v_add_u32_e32 v3, 0x20000, v3
	global_load_dword v8, v3, s[14:15]
	v_add_u32_e32 v3, 0x20000, v3
	global_load_dword v9, v3, s[14:15]
	v_add_u32_e32 v3, 0x20000, v3
	global_load_dword v10, v3, s[14:15]
	v_add_u32_e32 v3, 0x20000, v3
	global_load_dword v11, v3, s[14:15]
	v_add_u32_e32 v3, 0x20000, v3
	global_load_dword v12, v3, s[14:15]
	v_add_u32_e32 v3, 0x20000, v3
	global_load_dword v13, v3, s[14:15]
	v_add_u32_e32 v3, 0x20000, v3
	global_load_dword v14, v3, s[14:15]
	v_add_u32_e32 v3, 0x20000, v3
	global_load_dword v15, v3, s[14:15]
	v_add_u32_e32 v3, 0x20000, v3
	global_load_dword v16, v3, s[14:15]
	v_add_u32_e32 v3, 0x20000, v3
	global_load_dword v17, v3, s[14:15]
	v_add_u32_e32 v3, 0x20000, v3
	global_load_dword v18, v3, s[14:15]
	v_add_u32_e32 v3, 0x20000, v3
	global_load_dword v19, v3, s[14:15]
	s_add_i32 s5, s4, 2
	s_lshl_b32 s6, s5, 8
	s_add_i32 s6, s6, s2
	s_and_b32 s7, s6, 7
	s_mul_i32 s7, s7, 0x160
	s_lshr_b32 s20, s6, 3
	s_add_i32 s7, s7, s20
	s_lshr_b32 s20, s7, 3
	s_mul_i32 s20, s20, 0x1746
	s_lshr_b32 s20, s20, 16
	s_mul_i32 s21, s20, 0x58
	s_sub_i32 s21, s7, s21
	s_and_b32 s21, s21, 3
	s_lshl_b32 s20, s20, 2
	s_add_i32 s20, s20, s21
	s_lshl_b32 s20, s20, 10
	v_add_u32_e32 v3, s20, v2
	global_load_dword v20, v3, s[14:15]
	v_add_u32_e32 v3, 0x20000, v3
	global_load_dword v21, v3, s[14:15]
	v_add_u32_e32 v3, 0x20000, v3
	global_load_dword v22, v3, s[14:15]
	v_add_u32_e32 v3, 0x20000, v3
	global_load_dword v23, v3, s[14:15]
	v_add_u32_e32 v3, 0x20000, v3
	global_load_dword v24, v3, s[14:15]
	v_add_u32_e32 v3, 0x20000, v3
	global_load_dword v25, v3, s[14:15]
	v_add_u32_e32 v3, 0x20000, v3
	global_load_dword v26, v3, s[14:15]
	v_add_u32_e32 v3, 0x20000, v3
	global_load_dword v27, v3, s[14:15]
	v_add_u32_e32 v3, 0x20000, v3
	global_load_dword v28, v3, s[14:15]
	v_add_u32_e32 v3, 0x20000, v3
	global_load_dword v29, v3, s[14:15]
	v_add_u32_e32 v3, 0x20000, v3
	global_load_dword v30, v3, s[14:15]
	v_add_u32_e32 v3, 0x20000, v3
	global_load_dword v31, v3, s[14:15]
	v_add_u32_e32 v3, 0x20000, v3
	global_load_dword v32, v3, s[14:15]
	v_add_u32_e32 v3, 0x20000, v3
	global_load_dword v33, v3, s[14:15]
	v_add_u32_e32 v3, 0x20000, v3
	global_load_dword v34, v3, s[14:15]
	v_add_u32_e32 v3, 0x20000, v3
	global_load_dword v35, v3, s[14:15]
	s_add_i32 s5, s4, 4
	s_lshl_b32 s6, s5, 8
	s_add_i32 s6, s6, s2
	s_and_b32 s7, s6, 7
	s_mul_i32 s7, s7, 0x160
	s_lshr_b32 s20, s6, 3
	s_add_i32 s7, s7, s20
	s_lshr_b32 s20, s7, 3
	s_mul_i32 s20, s20, 0x1746
	s_lshr_b32 s20, s20, 16
	s_mul_i32 s21, s20, 0x58
	s_sub_i32 s21, s7, s21
	s_and_b32 s21, s21, 3
	s_lshl_b32 s20, s20, 2
	s_add_i32 s20, s20, s21
	s_lshl_b32 s20, s20, 10
	v_add_u32_e32 v3, s20, v2
	global_load_dword v36, v3, s[14:15]
	v_add_u32_e32 v3, 0x20000, v3
	global_load_dword v37, v3, s[14:15]
	v_add_u32_e32 v3, 0x20000, v3
	global_load_dword v38, v3, s[14:15]
	v_add_u32_e32 v3, 0x20000, v3
	global_load_dword v39, v3, s[14:15]
	v_add_u32_e32 v3, 0x20000, v3
	global_load_dword v40, v3, s[14:15]
	v_add_u32_e32 v3, 0x20000, v3
	global_load_dword v41, v3, s[14:15]
	v_add_u32_e32 v3, 0x20000, v3
	global_load_dword v42, v3, s[14:15]
	v_add_u32_e32 v3, 0x20000, v3
	global_load_dword v43, v3, s[14:15]
	v_add_u32_e32 v3, 0x20000, v3
	global_load_dword v44, v3, s[14:15]
	v_add_u32_e32 v3, 0x20000, v3
	global_load_dword v45, v3, s[14:15]
	v_add_u32_e32 v3, 0x20000, v3
	global_load_dword v46, v3, s[14:15]
	v_add_u32_e32 v3, 0x20000, v3
	global_load_dword v47, v3, s[14:15]
	v_add_u32_e32 v3, 0x20000, v3
	global_load_dword v48, v3, s[14:15]
	v_add_u32_e32 v3, 0x20000, v3
	global_load_dword v49, v3, s[14:15]
	v_add_u32_e32 v3, 0x20000, v3
	global_load_dword v50, v3, s[14:15]
	v_add_u32_e32 v3, 0x20000, v3
	global_load_dword v51, v3, s[14:15]
	s_add_i32 s5, s4, 6
	s_lshl_b32 s6, s5, 8
	s_add_i32 s6, s6, s2
	s_and_b32 s7, s6, 7
	s_mul_i32 s7, s7, 0x160
	s_lshr_b32 s20, s6, 3
	s_add_i32 s7, s7, s20
	s_lshr_b32 s20, s7, 3
	s_mul_i32 s20, s20, 0x1746
	s_lshr_b32 s20, s20, 16
	s_mul_i32 s21, s20, 0x58
	s_sub_i32 s21, s7, s21
	s_and_b32 s21, s21, 3
	s_lshl_b32 s20, s20, 2
	s_add_i32 s20, s20, s21
	s_lshl_b32 s20, s20, 10
	v_add_u32_e32 v3, s20, v2
	global_load_dword v52, v3, s[14:15]
	v_add_u32_e32 v3, 0x20000, v3
	global_load_dword v53, v3, s[14:15]
	v_add_u32_e32 v3, 0x20000, v3
	global_load_dword v54, v3, s[14:15]
	v_add_u32_e32 v3, 0x20000, v3
	global_load_dword v55, v3, s[14:15]
	v_add_u32_e32 v3, 0x20000, v3
	global_load_dword v56, v3, s[14:15]
	v_add_u32_e32 v3, 0x20000, v3
	global_load_dword v57, v3, s[14:15]
	v_add_u32_e32 v3, 0x20000, v3
	global_load_dword v58, v3, s[14:15]
	v_add_u32_e32 v3, 0x20000, v3
	global_load_dword v59, v3, s[14:15]
	v_add_u32_e32 v3, 0x20000, v3
	global_load_dword v60, v3, s[14:15]
	v_add_u32_e32 v3, 0x20000, v3
	global_load_dword v61, v3, s[14:15]
	v_add_u32_e32 v3, 0x20000, v3
	global_load_dword v62, v3, s[14:15]
	v_add_u32_e32 v3, 0x20000, v3
	global_load_dword v63, v3, s[14:15]
	v_add_u32_e32 v3, 0x20000, v3
	global_load_dword v64, v3, s[14:15]
	v_add_u32_e32 v3, 0x20000, v3
	global_load_dword v65, v3, s[14:15]
	v_add_u32_e32 v3, 0x20000, v3
	global_load_dword v66, v3, s[14:15]
	v_add_u32_e32 v3, 0x20000, v3
	global_load_dword v67, v3, s[14:15]
	s_add_i32 s5, s4, 8
	s_lshl_b32 s6, s5, 8
	s_add_i32 s6, s6, s2
	s_and_b32 s7, s6, 7
	s_mul_i32 s7, s7, 0x160
	s_lshr_b32 s20, s6, 3
	s_add_i32 s7, s7, s20
	s_lshr_b32 s20, s7, 3
	s_mul_i32 s20, s20, 0x1746
	s_lshr_b32 s20, s20, 16
	s_mul_i32 s21, s20, 0x58
	s_sub_i32 s21, s7, s21
	s_and_b32 s21, s21, 3
	s_lshl_b32 s20, s20, 2
	s_add_i32 s20, s20, s21
	s_lshl_b32 s20, s20, 10
	v_add_u32_e32 v3, s20, v2
	global_load_dword v68, v3, s[14:15]
	v_add_u32_e32 v3, 0x20000, v3
	global_load_dword v69, v3, s[14:15]
	v_add_u32_e32 v3, 0x20000, v3
	global_load_dword v70, v3, s[14:15]
	v_add_u32_e32 v3, 0x20000, v3
	global_load_dword v71, v3, s[14:15]
	v_add_u32_e32 v3, 0x20000, v3
	global_load_dword v72, v3, s[14:15]
	v_add_u32_e32 v3, 0x20000, v3
	global_load_dword v73, v3, s[14:15]
	v_add_u32_e32 v3, 0x20000, v3
	global_load_dword v74, v3, s[14:15]
	v_add_u32_e32 v3, 0x20000, v3
	global_load_dword v75, v3, s[14:15]
	v_add_u32_e32 v3, 0x20000, v3
	global_load_dword v76, v3, s[14:15]
	v_add_u32_e32 v3, 0x20000, v3
	global_load_dword v77, v3, s[14:15]
	v_add_u32_e32 v3, 0x20000, v3
	global_load_dword v78, v3, s[14:15]
	v_add_u32_e32 v3, 0x20000, v3
	global_load_dword v79, v3, s[14:15]
	v_add_u32_e32 v3, 0x20000, v3
	global_load_dword v80, v3, s[14:15]
	v_add_u32_e32 v3, 0x20000, v3
	global_load_dword v81, v3, s[14:15]
	v_add_u32_e32 v3, 0x20000, v3
	global_load_dword v82, v3, s[14:15]
	v_add_u32_e32 v3, 0x20000, v3
	global_load_dword v83, v3, s[14:15]
	s_add_i32 s5, s4, 10
	s_lshl_b32 s6, s5, 8
	s_add_i32 s6, s6, s2
	s_and_b32 s7, s6, 7
	s_mul_i32 s7, s7, 0x160
	s_lshr_b32 s20, s6, 3
	s_add_i32 s7, s7, s20
	s_lshr_b32 s20, s7, 3
	s_mul_i32 s20, s20, 0x1746
	s_lshr_b32 s20, s20, 16
	s_mul_i32 s21, s20, 0x58
	s_sub_i32 s21, s7, s21
	s_and_b32 s21, s21, 3
	s_lshl_b32 s20, s20, 2
	s_add_i32 s20, s20, s21
	s_lshl_b32 s20, s20, 10
	v_add_u32_e32 v3, s20, v2
	global_load_dword v84, v3, s[14:15]
	v_add_u32_e32 v3, 0x20000, v3
	global_load_dword v85, v3, s[14:15]
	v_add_u32_e32 v3, 0x20000, v3
	global_load_dword v86, v3, s[14:15]
	v_add_u32_e32 v3, 0x20000, v3
	global_load_dword v87, v3, s[14:15]
	v_add_u32_e32 v3, 0x20000, v3
	global_load_dword v88, v3, s[14:15]
	v_add_u32_e32 v3, 0x20000, v3
	global_load_dword v89, v3, s[14:15]
	v_add_u32_e32 v3, 0x20000, v3
	global_load_dword v90, v3, s[14:15]
	v_add_u32_e32 v3, 0x20000, v3
	global_load_dword v91, v3, s[14:15]
	v_add_u32_e32 v3, 0x20000, v3
	global_load_dword v92, v3, s[14:15]
	v_add_u32_e32 v3, 0x20000, v3
	global_load_dword v93, v3, s[14:15]
	v_add_u32_e32 v3, 0x20000, v3
	global_load_dword v94, v3, s[14:15]
	v_add_u32_e32 v3, 0x20000, v3
	global_load_dword v95, v3, s[14:15]
	v_add_u32_e32 v3, 0x20000, v3
	global_load_dword v96, v3, s[14:15]
	v_add_u32_e32 v3, 0x20000, v3
	global_load_dword v97, v3, s[14:15]
	v_add_u32_e32 v3, 0x20000, v3
	global_load_dword v98, v3, s[14:15]
	v_add_u32_e32 v3, 0x20000, v3
	global_load_dword v99, v3, s[14:15]
	s_waitcnt vmcnt(0)
	v_add_f32_e32 v4, v4, v5
	v_add_f32_e32 v4, v4, v6
	v_add_f32_e32 v4, v4, v7
	v_add_f32_e32 v8, v8, v9
	v_add_f32_e32 v8, v8, v10
	v_add_f32_e32 v8, v8, v11
	v_add_f32_e32 v12, v12, v13
	v_add_f32_e32 v12, v12, v14
	v_add_f32_e32 v12, v12, v15
	v_add_f32_e32 v16, v16, v17
	v_add_f32_e32 v16, v16, v18
	v_add_f32_e32 v16, v16, v19
	v_add_f32_e32 v4, v4, v8
	v_add_f32_e32 v12, v12, v16
	v_add_f32_e32 v4, v4, v12
	v_fma_f32 v4, v4, s90, v212
	v_rsq_f32_e32 v4, v4
	s_add_i32 s5, s4, 0
	s_lshl_b32 s5, s5, 10
	s_add_i32 s5, s5, 0x21000
	v_add_u32_e32 v3, s5, v2
	ds_write_b32 v3, v4
	v_add_f32_e32 v20, v20, v21
	v_add_f32_e32 v20, v20, v22
	v_add_f32_e32 v20, v20, v23
	v_add_f32_e32 v24, v24, v25
	v_add_f32_e32 v24, v24, v26
	v_add_f32_e32 v24, v24, v27
	v_add_f32_e32 v28, v28, v29
	v_add_f32_e32 v28, v28, v30
	v_add_f32_e32 v28, v28, v31
	v_add_f32_e32 v32, v32, v33
	v_add_f32_e32 v32, v32, v34
	v_add_f32_e32 v32, v32, v35
	v_add_f32_e32 v20, v20, v24
	v_add_f32_e32 v28, v28, v32
	v_add_f32_e32 v20, v20, v28
	v_fma_f32 v20, v20, s90, v212
	v_rsq_f32_e32 v20, v20
	s_add_i32 s5, s4, 2
	s_lshl_b32 s5, s5, 10
	s_add_i32 s5, s5, 0x21000
	v_add_u32_e32 v3, s5, v2
	ds_write_b32 v3, v20
	v_add_f32_e32 v36, v36, v37
	v_add_f32_e32 v36, v36, v38
	v_add_f32_e32 v36, v36, v39
	v_add_f32_e32 v40, v40, v41
	v_add_f32_e32 v40, v40, v42
	v_add_f32_e32 v40, v40, v43
	v_add_f32_e32 v44, v44, v45
	v_add_f32_e32 v44, v44, v46
	v_add_f32_e32 v44, v44, v47
	v_add_f32_e32 v48, v48, v49
	v_add_f32_e32 v48, v48, v50
	v_add_f32_e32 v48, v48, v51
	v_add_f32_e32 v36, v36, v40
	v_add_f32_e32 v44, v44, v48
	v_add_f32_e32 v36, v36, v44
	v_fma_f32 v36, v36, s90, v212
	v_rsq_f32_e32 v36, v36
	s_add_i32 s5, s4, 4
	s_lshl_b32 s5, s5, 10
	s_add_i32 s5, s5, 0x21000
	v_add_u32_e32 v3, s5, v2
	ds_write_b32 v3, v36
	v_add_f32_e32 v52, v52, v53
	v_add_f32_e32 v52, v52, v54
	v_add_f32_e32 v52, v52, v55
	v_add_f32_e32 v56, v56, v57
	v_add_f32_e32 v56, v56, v58
	v_add_f32_e32 v56, v56, v59
	v_add_f32_e32 v60, v60, v61
	v_add_f32_e32 v60, v60, v62
	v_add_f32_e32 v60, v60, v63
	v_add_f32_e32 v64, v64, v65
	v_add_f32_e32 v64, v64, v66
	v_add_f32_e32 v64, v64, v67
	v_add_f32_e32 v52, v52, v56
	v_add_f32_e32 v60, v60, v64
	v_add_f32_e32 v52, v52, v60
	v_fma_f32 v52, v52, s90, v212
	v_rsq_f32_e32 v52, v52
	s_add_i32 s5, s4, 6
	s_lshl_b32 s5, s5, 10
	s_add_i32 s5, s5, 0x21000
	v_add_u32_e32 v3, s5, v2
	ds_write_b32 v3, v52
	v_add_f32_e32 v68, v68, v69
	v_add_f32_e32 v68, v68, v70
	v_add_f32_e32 v68, v68, v71
	v_add_f32_e32 v72, v72, v73
	v_add_f32_e32 v72, v72, v74
	v_add_f32_e32 v72, v72, v75
	v_add_f32_e32 v76, v76, v77
	v_add_f32_e32 v76, v76, v78
	v_add_f32_e32 v76, v76, v79
	v_add_f32_e32 v80, v80, v81
	v_add_f32_e32 v80, v80, v82
	v_add_f32_e32 v80, v80, v83
	v_add_f32_e32 v68, v68, v72
	v_add_f32_e32 v76, v76, v80
	v_add_f32_e32 v68, v68, v76
	v_fma_f32 v68, v68, s90, v212
	v_rsq_f32_e32 v68, v68
	s_add_i32 s5, s4, 8
	s_lshl_b32 s5, s5, 10
	s_add_i32 s5, s5, 0x21000
	v_add_u32_e32 v3, s5, v2
	ds_write_b32 v3, v68
	v_add_f32_e32 v84, v84, v85
	v_add_f32_e32 v84, v84, v86
	v_add_f32_e32 v84, v84, v87
	v_add_f32_e32 v88, v88, v89
	v_add_f32_e32 v88, v88, v90
	v_add_f32_e32 v88, v88, v91
	v_add_f32_e32 v92, v92, v93
	v_add_f32_e32 v92, v92, v94
	v_add_f32_e32 v92, v92, v95
	v_add_f32_e32 v96, v96, v97
	v_add_f32_e32 v96, v96, v98
	v_add_f32_e32 v96, v96, v99
	v_add_f32_e32 v84, v84, v88
	v_add_f32_e32 v92, v92, v96
	v_add_f32_e32 v84, v84, v92
	v_fma_f32 v84, v84, s90, v212
	v_rsq_f32_e32 v84, v84
	s_add_i32 s5, s4, 10
	s_lshl_b32 s5, s5, 10
	s_add_i32 s5, s5, 0x21000
	v_add_u32_e32 v3, s5, v2
	ds_write_b32 v3, v84
	s_waitcnt lgkmcnt(0)
	v_lshlrev_b32_e32 v0, 4, v248
	s_waitcnt vmcnt(0)
	v_add_u32_e32 v2, 0x2000, v0
	s_waitcnt vmcnt(4)
	v_ashrrev_i32_e32 v3, 31, v2
	v_lshrrev_b32_e32 v3, 22, v3
	v_add_u32_e32 v3, v2, v3
	v_ashrrev_i32_e32 v10, 10, v3
	v_mul_i32_i24_e32 v3, 0x400, v10
	v_sub_u32_e32 v2, v2, v3
	v_lshrrev_b32_e32 v3, 4, v2
	v_bitop3_b32 v2, v3, v2, 32 bitop3:0x6c
	v_ashrrev_i32_e32 v3, 31, v2
	s_mul_i32 s5, s16, 0xb00000
	v_lshrrev_b32_e32 v3, 26, v3
	s_mul_hi_i32 s4, s16, 0xb00000
	s_add_u32 s5, s8, s5
	v_add_u32_e32 v3, v2, v3
	v_lshlrev_b32_e32 v5, 3, v10
	s_addc_u32 s4, s9, s4
	v_ashrrev_i32_e32 v4, 6, v3
	v_and_b32_e32 v5, -16, v5
	v_and_b32_e32 v3, 0xc0, v3
	s_add_u32 s17, s5, 0x1000000
	v_add_u32_e32 v5, v4, v5
	v_sub_u32_e32 v2, v2, v3
	s_addc_u32 s70, s4, 0
	v_lshlrev_b32_e32 v6, 1, v5
	v_lshlrev_b32_e32 v7, 3, v5
	v_lshlrev_b32_e32 v8, 5, v10
	v_ashrrev_i16_sdwa v2, v214, sext(v2) dst_sel:DWORD dst_unused:UNUSED_PAD src0_sel:DWORD src1_sel:BYTE_0
	v_and_b32_e32 v3, 3, v4
	s_mov_b32 s4, 0x1fffe0
	v_lshrrev_b32_e32 v4, 2, v5
	v_and_b32_e32 v11, 0x1fff80, v6
	v_and_b32_e32 v12, 0x78, v7
	v_bfe_u32 v13, v5, 4, 2
	v_and_b32_e32 v8, 32, v8
	v_bfe_i32 v14, v2, 0, 16
	v_and_or_b32 v3, v5, s4, v3
	v_and_b32_e32 v4, 4, v4
	v_and_b32_e32 v5, 24, v6
	v_or3_b32 v7, v11, v12, v13
	v_add_lshl_u32 v2, v8, v14, 1
	v_or3_b32 v3, v3, v4, v5
	v_lshl_add_u32 v222, v7, 11, v2
	v_lshl_add_u32 v224, v3, 11, v2
	v_bfe_i32 v2, v248, 27, 1
	v_lshrrev_b32_e32 v2, 22, v2
	v_add_u32_e32 v2, v0, v2
	v_and_b32_e32 v2, 0xfffffc00, v2
	v_sub_u32_e32 v0, v0, v2
	v_lshrrev_b32_e32 v2, 4, v0
	v_ashrrev_i32_e32 v4, 31, v248
	v_bitop3_b32 v0, v2, v0, 32 bitop3:0x6c
	v_lshrrev_b32_e32 v4, 26, v4
	v_ashrrev_i32_e32 v2, 31, v0
	v_add_u32_e32 v4, v248, v4
	v_lshrrev_b32_e32 v2, 26, v2
	v_ashrrev_i32_e32 v15, 6, v4
	v_add_u32_e32 v2, v0, v2
	v_lshlrev_b32_e32 v4, 3, v15
	v_ashrrev_i32_e32 v3, 6, v2
	v_and_b32_e32 v4, -16, v4
	v_and_b32_e32 v2, 0xc0, v2
	s_ashr_i32 s29, s28, 6
	v_add_u32_e32 v4, v3, v4
	v_sub_u32_e32 v0, v0, v2
	v_and_b32_e32 v2, 3, v3
	s_ashr_i32 s71, s28, 8
	s_lshl_b32 s74, s29, 10
	v_lshlrev_b32_e32 v5, 1, v4
	v_lshlrev_b32_e32 v6, 3, v4
	v_lshlrev_b32_e32 v7, 5, v15
	v_ashrrev_i16_sdwa v0, v214, sext(v0) dst_sel:DWORD dst_unused:UNUSED_PAD src0_sel:DWORD src1_sel:BYTE_0
	v_and_or_b32 v2, v4, s4, v2
	v_lshrrev_b32_e32 v3, 2, v4
	v_readlane_b32 s4, v254, 54
	v_and_b32_e32 v16, 0x1fff80, v5
	v_and_b32_e32 v17, 0x78, v6
	s_waitcnt vmcnt(3)
	v_bfe_u32 v18, v4, 4, 2
	v_and_b32_e32 v7, 32, v7
	v_bfe_i32 v19, v0, 0, 16
	v_and_b32_e32 v3, 4, v3
	v_and_b32_e32 v4, 24, v5
	v_readlane_b32 s5, v254, 55
	s_add_u32 s38, s17, s4
	v_or3_b32 v6, v16, v17, v18
	v_add_lshl_u32 v0, v7, v19, 1
	v_or3_b32 v2, v2, v3, v4
	s_addc_u32 s39, s70, s5
	s_add_i32 s75, s74, 0
	v_lshl_add_u32 v226, v6, 11, v0
	v_lshl_add_u32 v0, v2, 11, v0
	s_add_i32 m0, s75, 0x10000
	v_writelane_b32 v255, s30, 15
	global_load_lds_dwordx4 v0, s[38:39]
	s_add_i32 m0, s75, 0x12000
	s_add_u32 s4, s38, 0x40000
	global_load_lds_dwordx4 v224, s[38:39]
	s_addc_u32 s5, s39, 0
	s_add_i32 m0, s75, 0x14000
	v_mov_b32_e32 v225, v1
	global_load_lds_dwordx4 v0, s[4:5]
	s_add_i32 m0, s75, 0x16000
	v_mov_b32_e32 v227, v1
	global_load_lds_dwordx4 v224, s[4:5]
	v_readlane_b32 s4, v255, 4
	v_readlane_b32 s5, v255, 5
	s_add_u32 s42, s12, s4
	s_addc_u32 s43, s13, s5
	s_add_i32 s76, s75, 0x2000
	s_mov_b32 m0, s75
	s_add_u32 s4, s42, 0x2000
	global_load_lds_dwordx4 v226, s[42:43]
	s_mov_b32 m0, s76
	s_addc_u32 s5, s43, 0
	s_add_i32 s77, s75, 0x4000
	global_load_lds_dwordx4 v222, s[42:43]
	s_mov_b32 m0, s77
	s_add_i32 s78, s75, 0x6000
	global_load_lds_dwordx4 v226, s[4:5]
	s_mov_b32 m0, s78
	s_cmp_eq_u32 s71, 1
	global_load_lds_dwordx4 v222, s[4:5]
	s_load_dwordx2 s[26:27], s[0:1], 0x48
	s_load_dword s79, s[88:89], 0x0
	s_cselect_b64 s[24:25], -1, 0
	s_cmp_lg_u32 s71, 1
	v_mov_b32_e32 v223, v1
	s_cselect_b64 s[44:45], -1, 0
	v_lshl_add_u64 v[8:9], s[38:39], 0, v[0:1]
	v_lshl_add_u64 v[6:7], s[38:39], 0, v[224:225]
	v_lshl_add_u64 v[4:5], s[42:43], 0, v[226:227]
	v_lshl_add_u64 v[2:3], s[42:43], 0, v[222:223]
	s_and_b64 vcc, exec, s[44:45]
	s_cbranch_vccnz .LBB0_384
	s_barrier

.LBB0_393:
	s_lshl_b32 s4, s27, 8
	v_mov_b32_e32 v167, v250
	v_mov_b32_e32 v166, v249
	s_add_i32 s4, s4, s96
	s_nop 0
	v_lshl_add_u32 v232, v166, 3, s4
	v_lshlrev_b32_e32 v154, 2, v167
	v_ashrrev_i32_e32 v233, 31, v232
	v_ashrrev_i32_e32 v155, 31, v154
	v_or_b32_e32 v138, 1, v154
	v_lshl_add_u64 v[156:157], v[232:233], 2, s[14:15]
	v_lshlrev_b64 v[130:131], 17, v[154:155]
	v_ashrrev_i32_e32 v139, 31, v138
	v_or_b32_e32 v146, 2, v154
	v_lshl_add_u64 v[134:135], v[156:157], 0, v[130:131]
	v_lshlrev_b64 v[138:139], 17, v[138:139]
	v_ashrrev_i32_e32 v147, 31, v146
	v_or_b32_e32 v154, 3, v154
	s_nop 0
	v_lshl_add_u64 v[142:143], v[156:157], 0, v[138:139]
	v_lshlrev_b64 v[146:147], 17, v[146:147]
	v_ashrrev_i32_e32 v155, 31, v154
	s_nop 0
	v_lshl_add_u64 v[150:151], v[156:157], 0, v[146:147]
	v_lshlrev_b64 v[154:155], 17, v[154:155]
	s_nop 0
	v_lshl_add_u64 v[158:159], v[156:157], 0, v[154:155]
	s_nop 0
	s_add_i32 s4, s58, -1
	s_lshl_b32 s4, s4, 10
	s_add_i32 s4, s4, 0x21000
	v_lshrrev_b32_e32 v136, 8, v248
	v_lshlrev_b32_e32 v136, 9, v136
	v_lshl_add_u32 v136, v249, 5, v136
	v_add_u32_e32 v136, s4, v136
	ds_read_b32 v134, v136
	ds_read_b32 v135, v136 offset:4
	ds_read_b32 v240, v136 offset:8
	ds_read_b32 v242, v136 offset:12
	ds_read_b32 v236, v136 offset:16
	ds_read_b32 v238, v136 offset:20
	ds_read_b32 v130, v136 offset:24
	ds_read_b32 v131, v136 offset:28
	s_waitcnt lgkmcnt(0)
	v_lshl_add_u32 v138, v167, 3, s89
	v_ashrrev_i32_e32 v139, 31, v138
	s_waitcnt lgkmcnt(0)
	s_waitcnt lgkmcnt(0)
	s_nop 0
	s_nop 0
	s_nop 0
	s_nop 0
	v_pk_mul_f32 v[116:117], v[116:117], v[134:135] op_sel_hi:[1,0]
	v_pk_mul_f32 v[114:115], v[114:115], v[134:135] op_sel_hi:[1,0]
	v_pk_mul_f32 v[124:125], v[124:125], v[134:135] op_sel_hi:[1,0]
	v_pk_mul_f32 v[122:123], v[122:123], v[134:135] op_sel_hi:[1,0]
	v_pk_mul_f32 v[108:109], v[108:109], v[134:135] op_sel_hi:[1,0]
	v_pk_mul_f32 v[106:107], v[106:107], v[134:135] op_sel_hi:[1,0]
	v_pk_mul_f32 v[44:45], v[44:45], v[134:135] op_sel_hi:[1,0]
	v_pk_mul_f32 v[42:43], v[42:43], v[134:135] op_sel_hi:[1,0]
	s_nop 0
	v_mov_b32_e32 v134, v135
	v_pk_mul_f32 v[120:121], v[120:121], v[134:135] op_sel_hi:[1,0]
	v_pk_mul_f32 v[118:119], v[118:119], v[134:135] op_sel_hi:[1,0]
	v_pk_mul_f32 v[128:129], v[128:129], v[134:135] op_sel_hi:[1,0]
	v_pk_mul_f32 v[126:127], v[126:127], v[134:135] op_sel_hi:[1,0]
	v_pk_mul_f32 v[112:113], v[112:113], v[134:135] op_sel_hi:[1,0]
	v_pk_mul_f32 v[110:111], v[110:111], v[134:135] op_sel_hi:[1,0]
	v_pk_mul_f32 v[48:49], v[48:49], v[134:135] op_sel_hi:[1,0]
	v_pk_mul_f32 v[46:47], v[46:47], v[134:135] op_sel_hi:[1,0]
	s_nop 0
	s_nop 0
	s_nop 0
	s_waitcnt lgkmcnt(0)
	s_waitcnt lgkmcnt(2)
	v_or_b32_e32 v134, s71, v166
	v_cmp_eq_u32_e32 vcc, 0, v134
	s_waitcnt lgkmcnt(0)
	s_and_saveexec_b64 s[38:39], vcc
	s_cbranch_execz .LBB0_395
	s_lshl_b32 s4, s26, 8
	s_ashr_i32 s5, s4, 31
	s_mul_i32 s7, s27, 0x16000
	s_mul_hi_i32 s6, s27, 0x16000
	s_add_u32 s7, s84, s7
	s_addc_u32 s6, s88, s6
	s_lshl_b64 s[4:5], s[4:5], 2
	s_add_u32 s4, s7, s4
	s_addc_u32 s5, s6, s5
	v_lshl_add_u64 v[134:135], v[138:139], 2, s[4:5]
	s_mov_b64 s[4:5], 0x5800
	global_store_dwordx4 v[134:135], v[114:117], off
	global_store_dwordx4 v[134:135], v[122:125], off offset:16
	global_store_dwordx4 v[134:135], v[106:109], off offset:512
	global_store_dwordx4 v[134:135], v[42:45], off offset:528
	v_lshl_add_u64 v[136:137], v[134:135], 0, s[4:5]
	v_add_co_u32_e32 v134, vcc, 0x5000, v134
	s_nop 1
	v_addc_co_u32_e32 v135, vcc, 0, v135, vcc
	global_store_dwordx4 v[134:135], v[118:121], off offset:2048
	global_store_dwordx4 v[136:137], v[126:129], off offset:16
	global_store_dwordx4 v[136:137], v[110:113], off offset:512
	global_store_dwordx4 v[136:137], v[46:49], off offset:528
.LBB0_395:
	s_or_b64 exec, exec, s[38:39]
	s_waitcnt lgkmcnt(0)
	s_nop 0
	s_nop 0
	s_nop 1
	s_nop 0
	v_pk_mul_f32 v[136:137], v[104:105], v[130:131] op_sel_hi:[1,0]
	v_pk_mul_f32 v[104:105], v[88:89], v[130:131] op_sel_hi:[1,0]
	v_pk_mul_f32 v[134:135], v[102:103], v[130:131] op_sel_hi:[1,0]
	v_pk_mul_f32 v[102:103], v[86:87], v[130:131] op_sel_hi:[1,0]
	v_pk_mul_f32 v[156:157], v[100:101], v[130:131] op_sel_hi:[1,0]
	v_pk_mul_f32 v[154:155], v[98:99], v[130:131] op_sel_hi:[1,0]
	v_pk_mul_f32 v[84:85], v[84:85], v[130:131] op_sel_hi:[1,0]
	v_mov_b32_e32 v86, v131
	v_pk_mul_f32 v[82:83], v[82:83], v[130:131] op_sel_hi:[1,0]
	v_pk_mul_f32 v[144:145], v[96:97], v[86:87] op_sel_hi:[1,0]
	v_pk_mul_f32 v[142:143], v[94:95], v[86:87] op_sel_hi:[1,0]
	v_pk_mul_f32 v[180:181], v[92:93], v[86:87] op_sel_hi:[1,0]
	v_pk_mul_f32 v[178:179], v[90:91], v[86:87] op_sel_hi:[1,0]
	v_pk_mul_f32 v[132:133], v[80:81], v[86:87] op_sel_hi:[1,0]
	v_pk_mul_f32 v[130:131], v[78:79], v[86:87] op_sel_hi:[1,0]
	v_pk_mul_f32 v[76:77], v[76:77], v[86:87] op_sel_hi:[1,0]
	v_pk_mul_f32 v[74:75], v[74:75], v[86:87] op_sel_hi:[1,0]
	v_cmp_eq_u32_e32 vcc, 15, v166
	s_and_saveexec_b64 s[38:39], vcc
	s_cbranch_execz .LBB0_400
	s_andn2_b64 vcc, exec, s[44:45]
	s_mov_b64 s[42:43], -1
	s_cbranch_vccnz .LBB0_398
	v_lshl_add_u32 v78, v167, 7, s97
	s_mov_b64 s[42:43], 0
	ds_write_b128 v78, v[134:137]
	ds_write_b128 v78, v[154:157] offset:16
	ds_write_b128 v78, v[102:105] offset:32
	ds_write_b128 v78, v[82:85] offset:48
	ds_write_b128 v78, v[142:145] offset:64
	ds_write_b128 v78, v[178:181] offset:80
	ds_write_b128 v78, v[130:133] offset:96
	ds_write_b128 v78, v[74:77] offset:112

.LBB0_408:
	s_or_b64 exec, exec, s[38:39]
	s_mov_b32 s4, 0x358637bd
	v_mov_b64_e32 v[214:215], s[4:5]
	s_mov_b64 s[26:27], -1
	v_pk_mul_f32 v[16:17], v[16:17], v[240:241] op_sel_hi:[1,0]
	v_pk_mul_f32 v[220:221], v[68:69], v[242:243] op_sel_hi:[1,0]
	v_pk_mul_f32 v[218:219], v[66:67], v[242:243] op_sel_hi:[1,0]
	v_pk_mul_f32 v[216:217], v[72:73], v[240:241] op_sel_hi:[1,0]
	v_pk_mul_f32 v[72:73], v[64:65], v[236:237] op_sel_hi:[1,0]
	s_waitcnt vmcnt(3)
	v_pk_mul_f32 v[64:65], v[154:155], v[198:199]
	v_pk_mul_f32 v[68:69], v[60:61], v[238:239] op_sel_hi:[1,0]
	v_pk_mul_f32 v[60:61], v[178:179], v[198:199]
	v_pk_mul_f32 v[66:67], v[58:59], v[238:239] op_sel_hi:[1,0]
	v_pk_mul_f32 v[58:59], v[180:181], v[200:201]
	v_pk_fma_f32 v[60:61], v[154:155], v[194:195], v[60:61]
	v_pk_mul_f32 v[214:215], v[70:71], v[240:241] op_sel_hi:[1,0]
	v_pk_mul_f32 v[70:71], v[62:63], v[236:237] op_sel_hi:[1,0]
	v_pk_fma_f32 v[58:59], v[156:157], v[196:197], v[58:59]
	v_pk_fma_f32 v[60:61], v[66:67], v[190:191], v[60:61]
	v_pk_mul_f32 v[62:63], v[156:157], v[200:201]
	v_pk_fma_f32 v[64:65], v[66:67], v[194:195], v[64:65]
	v_pk_mul_f32 v[66:67], v[66:67], v[198:199]
	v_pk_fma_f32 v[58:59], v[68:69], v[192:193], v[58:59]
	v_pk_fma_f32 v[62:63], v[68:69], v[196:197], v[62:63]
	v_pk_fma_f32 v[64:65], v[70:71], v[190:191], v[64:65]
	v_pk_mul_f32 v[68:69], v[68:69], v[200:201]
	v_pk_fma_f32 v[154:155], v[70:71], v[194:195], v[66:67]
	v_pk_mul_f32 v[70:71], v[70:71], v[198:199]
	v_pk_fma_f32 v[62:63], v[72:73], v[192:193], v[62:63]
	v_pk_fma_f32 v[66:67], v[72:73], v[196:197], v[68:69]
	v_pk_fma_f32 v[68:69], v[218:219], v[190:191], v[154:155]
	v_pk_mul_f32 v[72:73], v[72:73], v[200:201]
	v_pk_fma_f32 v[154:155], v[218:219], v[194:195], v[70:71]
	v_pk_fma_f32 v[70:71], v[220:221], v[196:197], v[72:73]
	v_pk_fma_f32 v[72:73], v[214:215], v[190:191], v[154:155]
	v_pk_mul_f32 v[154:155], v[220:221], v[200:201]
	v_pk_mul_f32 v[156:157], v[218:219], v[198:199]
	v_pk_fma_f32 v[154:155], v[216:217], v[196:197], v[154:155]
	v_pk_fma_f32 v[156:157], v[214:215], v[194:195], v[156:157]
	v_pk_mul_f32 v[178:179], v[216:217], v[200:201]
	v_pk_mul_f32 v[180:181], v[214:215], v[198:199]
	v_pk_fma_f32 v[154:155], v[128:129], v[192:193], v[154:155]
	v_pk_fma_f32 v[156:157], v[126:127], v[190:191], v[156:157]
	v_pk_fma_f32 v[180:181], v[126:127], v[194:195], v[180:181]
	v_pk_fma_f32 v[178:179], v[128:129], v[196:197], v[178:179]
	v_pk_mul_f32 v[128:129], v[128:129], v[200:201]
	v_pk_mul_f32 v[126:127], v[126:127], v[198:199]
	v_pk_fma_f32 v[128:129], v[124:125], v[196:197], v[128:129]
	v_pk_fma_f32 v[214:215], v[122:123], v[194:195], v[126:127]
	s_waitcnt lgkmcnt(0)
	v_pk_mul_f32 v[196:197], v[196:197], v[204:205]
	v_pk_mul_f32 v[194:195], v[194:195], v[202:203]
	v_pk_fma_f32 v[178:179], v[124:125], v[192:193], v[178:179]
	v_pk_fma_f32 v[124:125], v[124:125], v[200:201], v[196:197]
	v_pk_fma_f32 v[194:195], v[122:123], v[198:199], v[194:195]
	v_pk_mul_f32 v[198:199], v[38:39], v[236:237] op_sel_hi:[1,0]
	v_pk_mul_f32 v[200:201], v[40:41], v[236:237] op_sel_hi:[1,0]
	v_pk_mul_f32 v[38:39], v[144:145], v[176:177]
	v_pk_mul_f32 v[40:41], v[142:143], v[174:175]
	v_pk_mul_f32 v[34:35], v[34:35], v[238:239] op_sel_hi:[1,0]
	v_pk_mul_f32 v[36:37], v[36:37], v[238:239] op_sel_hi:[1,0]
	v_pk_fma_f32 v[38:39], v[136:137], v[164:165], v[38:39]
	v_pk_fma_f32 v[40:41], v[134:135], v[162:163], v[40:41]
	v_pk_fma_f32 v[66:67], v[220:221], v[192:193], v[66:67]
	v_pk_fma_f32 v[70:71], v[216:217], v[192:193], v[70:71]
	v_pk_fma_f32 v[180:181], v[122:123], v[190:191], v[180:181]
	v_pk_fma_f32 v[126:127], v[192:193], v[204:205], v[128:129]
	v_pk_fma_f32 v[128:129], v[190:191], v[202:203], v[214:215]
	v_pk_fma_f32 v[122:123], v[192:193], v[208:209], v[124:125]
	v_pk_fma_f32 v[124:125], v[190:191], v[206:207], v[194:195]
	v_pk_mul_f32 v[190:191], v[54:55], v[240:241] op_sel_hi:[1,0]
	v_pk_mul_f32 v[192:193], v[56:57], v[240:241] op_sel_hi:[1,0]
	v_pk_fma_f32 v[56:57], v[36:37], v[160:161], v[38:39]
	v_pk_fma_f32 v[54:55], v[34:35], v[158:159], v[40:41]
	v_pk_mul_f32 v[38:39], v[136:137], v[176:177]
	v_pk_mul_f32 v[40:41], v[134:135], v[174:175]
	v_pk_fma_f32 v[38:39], v[36:37], v[164:165], v[38:39]
	v_pk_fma_f32 v[40:41], v[34:35], v[162:163], v[40:41]
	v_pk_mul_f32 v[36:37], v[36:37], v[176:177]
	v_pk_mul_f32 v[34:35], v[34:35], v[174:175]
	v_pk_mul_f32 v[194:195], v[50:51], v[242:243] op_sel_hi:[1,0]
	v_pk_mul_f32 v[196:197], v[52:53], v[242:243] op_sel_hi:[1,0]
	v_pk_fma_f32 v[34:35], v[198:199], v[162:163], v[34:35]
	v_pk_fma_f32 v[36:37], v[200:201], v[164:165], v[36:37]
	v_pk_fma_f32 v[52:53], v[200:201], v[160:161], v[38:39]
	v_pk_fma_f32 v[50:51], v[198:199], v[158:159], v[40:41]
	v_pk_fma_f32 v[40:41], v[196:197], v[160:161], v[36:37]
	v_pk_fma_f32 v[38:39], v[194:195], v[158:159], v[34:35]
	v_pk_mul_f32 v[34:35], v[200:201], v[176:177]
	v_pk_mul_f32 v[36:37], v[198:199], v[174:175]
	v_pk_fma_f32 v[34:35], v[196:197], v[164:165], v[34:35]
	v_pk_fma_f32 v[134:135], v[194:195], v[162:163], v[36:37]
	v_pk_mul_f32 v[136:137], v[194:195], v[174:175]
	v_pk_fma_f32 v[36:37], v[192:193], v[160:161], v[34:35]
	v_pk_fma_f32 v[34:35], v[190:191], v[158:159], v[134:135]
	v_pk_mul_f32 v[134:135], v[196:197], v[176:177]
	v_pk_fma_f32 v[136:137], v[190:191], v[162:163], v[136:137]
	v_pk_mul_f32 v[144:145], v[190:191], v[174:175]
	v_pk_fma_f32 v[134:135], v[192:193], v[164:165], v[134:135]
	v_pk_fma_f32 v[136:137], v[118:119], v[158:159], v[136:137]
	v_pk_mul_f32 v[142:143], v[192:193], v[176:177]
	v_pk_fma_f32 v[144:145], v[118:119], v[162:163], v[144:145]
	v_pk_mul_f32 v[118:119], v[118:119], v[174:175]
	v_pk_fma_f32 v[134:135], v[120:121], v[160:161], v[134:135]
	v_pk_fma_f32 v[142:143], v[120:121], v[164:165], v[142:143]
	v_pk_mul_f32 v[120:121], v[120:121], v[176:177]
	v_pk_fma_f32 v[118:119], v[114:115], v[162:163], v[118:119]
	v_pk_fma_f32 v[120:121], v[116:117], v[164:165], v[120:121]
	v_pk_fma_f32 v[192:193], v[158:159], v[182:183], v[118:119]
	v_pk_mul_f32 v[118:119], v[164:165], v[184:185]
	v_pk_mul_f32 v[164:165], v[30:31], v[240:241] op_sel_hi:[1,0]
	v_pk_mul_f32 v[30:31], v[132:133], v[152:153]
	v_pk_fma_f32 v[142:143], v[116:117], v[160:161], v[142:143]
	v_pk_fma_f32 v[116:117], v[116:117], v[176:177], v[118:119]
	v_pk_mul_f32 v[20:21], v[20:21], v[238:239] op_sel_hi:[1,0]
	v_pk_fma_f32 v[30:31], v[104:105], v[148:149], v[30:31]
	v_pk_fma_f32 v[190:191], v[160:161], v[184:185], v[120:121]
	v_pk_fma_f32 v[160:161], v[160:161], v[188:189], v[116:117]
	v_pk_fma_f32 v[116:117], v[20:21], v[140:141], v[30:31]
	v_pk_mul_f32 v[30:31], v[104:105], v[152:153]
	v_pk_mul_f32 v[120:121], v[162:163], v[182:183]
	v_pk_mul_f32 v[162:163], v[32:33], v[240:241] op_sel_hi:[1,0]
	v_pk_mul_f32 v[24:25], v[24:25], v[236:237] op_sel_hi:[1,0]
	v_pk_mul_f32 v[32:33], v[130:131], v[150:151]
	v_pk_fma_f32 v[30:31], v[20:21], v[148:149], v[30:31]
	v_pk_mul_f32 v[20:21], v[20:21], v[152:153]
	v_pk_fma_f32 v[144:145], v[114:115], v[158:159], v[144:145]
	v_pk_fma_f32 v[114:115], v[114:115], v[174:175], v[120:121]
	v_pk_mul_f32 v[28:29], v[28:29], v[242:243] op_sel_hi:[1,0]
	v_pk_mul_f32 v[18:19], v[18:19], v[238:239] op_sel_hi:[1,0]
	v_pk_fma_f32 v[32:33], v[102:103], v[146:147], v[32:33]
	v_pk_fma_f32 v[20:21], v[24:25], v[148:149], v[20:21]
	v_pk_fma_f32 v[158:159], v[158:159], v[186:187], v[114:115]
	v_pk_fma_f32 v[114:115], v[18:19], v[138:139], v[32:33]
	v_pk_mul_f32 v[32:33], v[102:103], v[150:151]
	v_pk_fma_f32 v[120:121], v[28:29], v[140:141], v[20:21]
	v_pk_mul_f32 v[20:21], v[24:25], v[152:153]
	v_pk_mul_f32 v[22:23], v[22:23], v[236:237] op_sel_hi:[1,0]
	v_pk_fma_f32 v[32:33], v[18:19], v[146:147], v[32:33]
	v_pk_mul_f32 v[18:19], v[18:19], v[150:151]
	v_pk_fma_f32 v[20:21], v[28:29], v[148:149], v[20:21]
	v_pk_mul_f32 v[26:27], v[26:27], v[242:243] op_sel_hi:[1,0]
	v_pk_fma_f32 v[18:19], v[22:23], v[146:147], v[18:19]
	v_pk_fma_f32 v[132:133], v[162:163], v[140:141], v[20:21]
	v_pk_mul_f32 v[20:21], v[28:29], v[152:153]
	v_pk_fma_f32 v[118:119], v[26:27], v[138:139], v[18:19]
	v_pk_mul_f32 v[18:19], v[22:23], v[150:151]
	v_pk_fma_f32 v[20:21], v[162:163], v[148:149], v[20:21]
	v_pk_fma_f32 v[102:103], v[22:23], v[138:139], v[32:33]
	v_pk_fma_f32 v[18:19], v[26:27], v[146:147], v[18:19]
	v_pk_fma_f32 v[32:33], v[112:113], v[140:141], v[20:21]
	v_pk_mul_f32 v[20:21], v[162:163], v[152:153]
	v_pk_fma_f32 v[130:131], v[164:165], v[138:139], v[18:19]
	v_pk_mul_f32 v[18:19], v[26:27], v[150:151]
	v_pk_fma_f32 v[20:21], v[112:113], v[148:149], v[20:21]
	v_pk_fma_f32 v[18:19], v[164:165], v[146:147], v[18:19]
	v_pk_fma_f32 v[28:29], v[108:109], v[140:141], v[20:21]
	v_pk_mul_f32 v[20:21], v[110:111], v[150:151]
	v_pk_fma_f32 v[104:105], v[24:25], v[140:141], v[30:31]
	v_pk_fma_f32 v[30:31], v[110:111], v[138:139], v[18:19]
	v_pk_mul_f32 v[18:19], v[164:165], v[150:151]
	v_pk_fma_f32 v[20:21], v[106:107], v[146:147], v[20:21]
	v_pk_fma_f32 v[18:19], v[110:111], v[146:147], v[18:19]
	v_pk_fma_f32 v[24:25], v[138:139], v[166:167], v[20:21]
	v_pk_mul_f32 v[20:21], v[146:147], v[166:167]
	v_pk_fma_f32 v[26:27], v[106:107], v[138:139], v[18:19]
	v_pk_fma_f32 v[20:21], v[106:107], v[150:151], v[20:21]
	v_pk_mul_f32 v[106:107], v[158:159], s[100:101] op_sel_hi:[1,0]
	v_exp_f32_e32 v106, v106
	v_exp_f32_e32 v107, v107
	v_pk_mul_f32 v[18:19], v[112:113], v[152:153]
	v_pk_fma_f32 v[20:21], v[138:139], v[170:171], v[20:21]
	v_pk_fma_f32 v[18:19], v[108:109], v[148:149], v[18:19]
	v_pk_add_f32 v[106:107], v[106:107], 1.0 op_sel_hi:[1,0]
	v_pk_fma_f32 v[22:23], v[140:141], v[168:169], v[18:19]
	v_pk_mul_f32 v[18:19], v[148:149], v[168:169]
	v_rcp_f32_e32 v106, v106
	v_rcp_f32_e32 v107, v107
	v_pk_fma_f32 v[18:19], v[108:109], v[152:153], v[18:19]
	v_pk_mul_f32 v[26:27], v[144:145], v[26:27]
	v_pk_fma_f32 v[18:19], v[140:141], v[172:173], v[18:19]
	v_pk_mul_f32 v[28:29], v[142:143], v[28:29]
	v_pk_mul_f32 v[108:109], v[160:161], v[18:19]
	v_pk_mul_f32 v[18:19], v[158:159], v[20:21]
	v_pk_mul_f32 v[20:21], v[160:161], s[100:101] op_sel_hi:[1,0]
	v_pk_mul_f32 v[18:19], v[106:107], v[18:19]
	v_exp_f32_e32 v20, v20
	v_exp_f32_e32 v21, v21
	v_pk_mul_f32 v[106:107], v[192:193], s[100:101] op_sel_hi:[1,0]
	v_exp_f32_e32 v106, v106
	v_exp_f32_e32 v107, v107
	v_pk_add_f32 v[20:21], v[20:21], 1.0 op_sel_hi:[1,0]
	v_rcp_f32_e32 v20, v20
	v_rcp_f32_e32 v21, v21
	v_pk_add_f32 v[106:107], v[106:107], 1.0 op_sel_hi:[1,0]
	v_rcp_f32_e32 v106, v106
	v_rcp_f32_e32 v107, v107
	v_pk_mul_f32 v[20:21], v[20:21], v[108:109]
	v_pk_mul_f32 v[108:109], v[190:191], v[22:23]
	v_pk_mul_f32 v[22:23], v[192:193], v[24:25]
	v_pk_mul_f32 v[30:31], v[136:137], v[30:31]
	v_pk_mul_f32 v[22:23], v[106:107], v[22:23]
	v_pk_mul_f32 v[106:107], v[144:145], s[100:101] op_sel_hi:[1,0]
	v_exp_f32_e32 v106, v106
	v_exp_f32_e32 v107, v107
	v_pk_mul_f32 v[24:25], v[190:191], s[100:101] op_sel_hi:[1,0]
	v_pk_add_f32 v[106:107], v[106:107], 1.0 op_sel_hi:[1,0]
	v_rcp_f32_e32 v106, v106
	v_rcp_f32_e32 v107, v107
	v_pk_mul_f32 v[32:33], v[134:135], v[32:33]
	v_exp_f32_e32 v24, v24
	v_exp_f32_e32 v25, v25
	v_pk_mul_f32 v[26:27], v[106:107], v[26:27]
	v_pk_mul_f32 v[106:107], v[142:143], s[100:101] op_sel_hi:[1,0]
	v_exp_f32_e32 v106, v106
	v_exp_f32_e32 v107, v107
	v_pk_add_f32 v[24:25], v[24:25], 1.0 op_sel_hi:[1,0]
	v_pk_add_f32 v[106:107], v[106:107], 1.0 op_sel_hi:[1,0]
	v_rcp_f32_e32 v106, v106
	v_rcp_f32_e32 v107, v107
	v_rcp_f32_e32 v24, v24
	v_rcp_f32_e32 v25, v25
	v_pk_mul_f32 v[104:105], v[52:53], v[104:105]
	v_pk_mul_f32 v[28:29], v[106:107], v[28:29]
	v_pk_mul_f32 v[106:107], v[136:137], s[100:101] op_sel_hi:[1,0]
	v_exp_f32_e32 v106, v106
	v_exp_f32_e32 v107, v107
	v_pk_mul_f32 v[24:25], v[24:25], v[108:109]
	v_pk_mul_f32 v[108:109], v[36:37], v[132:133]
	v_pk_add_f32 v[106:107], v[106:107], 1.0 op_sel_hi:[1,0]
	v_rcp_f32_e32 v106, v106
	v_rcp_f32_e32 v107, v107
	v_pk_mul_f32 v[36:37], v[36:37], s[100:101] op_sel_hi:[1,0]
	v_exp_f32_e32 v36, v36
	v_pk_mul_f32 v[30:31], v[106:107], v[30:31]
	v_pk_mul_f32 v[106:107], v[134:135], s[100:101] op_sel_hi:[1,0]
	v_exp_f32_e32 v106, v106
	v_exp_f32_e32 v107, v107
	v_exp_f32_e32 v37, v37
	v_mul_f32_e32 v52, 0xbfb8aa3b, v52
	v_pk_add_f32 v[106:107], v[106:107], 1.0 op_sel_hi:[1,0]
	v_rcp_f32_e32 v106, v106
	v_rcp_f32_e32 v107, v107
	v_mul_f32_e32 v53, 0xbfb8aa3b, v53
	v_exp_f32_e32 v52, v52
	v_exp_f32_e32 v53, v53
	v_pk_mul_f32 v[32:33], v[106:107], v[32:33]
	v_pk_mul_f32 v[106:107], v[34:35], s[100:101] op_sel_hi:[1,0]
	v_exp_f32_e32 v106, v106
	v_exp_f32_e32 v107, v107
	v_pk_mul_f32 v[34:35], v[34:35], v[130:131]
	v_add_f32_e32 v36, 1.0, v36
	v_pk_add_f32 v[106:107], v[106:107], 1.0 op_sel_hi:[1,0]
	v_rcp_f32_e32 v106, v106
	v_rcp_f32_e32 v107, v107
	v_add_f32_e32 v37, 1.0, v37
	v_rcp_f32_e32 v36, v36
	v_rcp_f32_e32 v37, v37
	v_pk_mul_f32 v[34:35], v[106:107], v[34:35]
	v_pk_mul_f32 v[106:107], v[38:39], s[100:101] op_sel_hi:[1,0]
	v_exp_f32_e32 v106, v106
	v_exp_f32_e32 v107, v107
	v_pk_add_f32 v[52:53], v[52:53], 1.0 op_sel_hi:[1,0]
	v_pk_add_f32 v[106:107], v[106:107], 1.0 op_sel_hi:[1,0]
	v_rcp_f32_e32 v106, v106
	v_rcp_f32_e32 v107, v107
	v_rcp_f32_e32 v52, v52
	v_rcp_f32_e32 v53, v53
	v_pk_mul_f32 v[36:37], v[36:37], v[108:109]
	v_pk_mul_f32 v[108:109], v[40:41], v[120:121]
	v_pk_mul_f32 v[38:39], v[38:39], v[118:119]
	v_pk_mul_f32 v[40:41], v[40:41], s[100:101] op_sel_hi:[1,0]
	v_pk_mul_f32 v[38:39], v[106:107], v[38:39]
	v_exp_f32_e32 v40, v40
	v_exp_f32_e32 v41, v41
	v_pk_mul_f32 v[106:107], v[50:51], s[100:101] op_sel_hi:[1,0]
	v_pk_mul_f32 v[50:51], v[50:51], v[102:103]
	v_pk_mul_f32 v[52:53], v[52:53], v[104:105]
	v_pk_mul_f32 v[102:103], v[54:55], s[100:101] op_sel_hi:[1,0]
	v_pk_mul_f32 v[104:105], v[56:57], v[116:117]
	v_pk_mul_f32 v[56:57], v[56:57], s[100:101] op_sel_hi:[1,0]
	v_exp_f32_e32 v102, v102
	v_exp_f32_e32 v103, v103
	v_exp_f32_e32 v56, v56
	v_exp_f32_e32 v57, v57
	v_exp_f32_e32 v106, v106
	v_exp_f32_e32 v107, v107
	v_pk_add_f32 v[40:41], v[40:41], 1.0 op_sel_hi:[1,0]
	v_rcp_f32_e32 v40, v40
	v_rcp_f32_e32 v41, v41
	v_pk_add_f32 v[102:103], v[102:103], 1.0 op_sel_hi:[1,0]
	v_pk_add_f32 v[56:57], v[56:57], 1.0 op_sel_hi:[1,0]
	v_rcp_f32_e32 v102, v102
	v_rcp_f32_e32 v103, v103
	v_rcp_f32_e32 v56, v56
	v_rcp_f32_e32 v57, v57
	v_pk_add_f32 v[106:107], v[106:107], 1.0 op_sel_hi:[1,0]
	v_rcp_f32_e32 v106, v106
	v_rcp_f32_e32 v107, v107
	v_pk_mul_f32 v[40:41], v[40:41], v[108:109]
	v_pk_mul_f32 v[54:55], v[54:55], v[114:115]
	v_pk_mul_f32 v[108:109], v[2:3], v[238:239] op_sel_hi:[1,0]
	s_waitcnt vmcnt(0)
	v_pk_mul_f32 v[2:3], v[76:77], v[92:93]
	v_pk_mul_f32 v[54:55], v[102:103], v[54:55]
	v_pk_mul_f32 v[56:57], v[56:57], v[104:105]
	v_pk_mul_f32 v[102:103], v[10:11], v[242:243] op_sel_hi:[1,0]
	v_pk_mul_f32 v[104:105], v[4:5], v[238:239] op_sel_hi:[1,0]
	v_pk_mul_f32 v[4:5], v[74:75], v[90:91]
	v_pk_fma_f32 v[10:11], v[84:85], v[88:89], v[2:3]
	v_pk_fma_f32 v[2:3], v[82:83], v[86:87], v[4:5]
	v_pk_fma_f32 v[4:5], v[104:105], v[80:81], v[10:11]
	v_pk_mul_f32 v[10:11], v[84:85], v[92:93]
	v_pk_mul_f32 v[50:51], v[106:107], v[50:51]
	v_pk_mul_f32 v[106:107], v[14:15], v[240:241] op_sel_hi:[1,0]
	v_pk_mul_f32 v[8:9], v[8:9], v[236:237] op_sel_hi:[1,0]
	v_pk_mul_f32 v[14:15], v[82:83], v[90:91]
	v_pk_fma_f32 v[74:75], v[104:105], v[88:89], v[10:11]
	v_pk_mul_f32 v[76:77], v[104:105], v[92:93]
	v_pk_mul_f32 v[12:13], v[12:13], v[242:243] op_sel_hi:[1,0]
	v_pk_fma_f32 v[10:11], v[108:109], v[86:87], v[14:15]
	v_pk_fma_f32 v[14:15], v[8:9], v[80:81], v[74:75]
	v_pk_fma_f32 v[76:77], v[8:9], v[88:89], v[76:77]
	v_pk_mul_f32 v[8:9], v[8:9], v[92:93]
	v_pk_mul_f32 v[6:7], v[6:7], v[236:237] op_sel_hi:[1,0]
	v_pk_fma_f32 v[8:9], v[12:13], v[88:89], v[8:9]
	v_pk_mul_f32 v[74:75], v[108:109], v[90:91]
	v_pk_fma_f32 v[84:85], v[16:17], v[80:81], v[8:9]
	v_pk_mul_f32 v[8:9], v[12:13], v[92:93]
	v_pk_fma_f32 v[10:11], v[6:7], v[78:79], v[10:11]
	v_pk_fma_f32 v[74:75], v[6:7], v[86:87], v[74:75]
	v_pk_mul_f32 v[6:7], v[6:7], v[90:91]
	v_pk_fma_f32 v[8:9], v[16:17], v[88:89], v[8:9]
	v_pk_fma_f32 v[6:7], v[102:103], v[86:87], v[6:7]
	v_pk_fma_f32 v[104:105], v[48:49], v[80:81], v[8:9]
	v_pk_mul_f32 v[8:9], v[16:17], v[92:93]
	v_pk_fma_f32 v[82:83], v[106:107], v[78:79], v[6:7]
	v_pk_mul_f32 v[6:7], v[102:103], v[90:91]
	v_pk_fma_f32 v[8:9], v[48:49], v[88:89], v[8:9]
	v_pk_fma_f32 v[2:3], v[108:109], v[78:79], v[2:3]
	v_pk_fma_f32 v[6:7], v[106:107], v[86:87], v[6:7]
	v_pk_fma_f32 v[108:109], v[44:45], v[80:81], v[8:9]
	v_pk_mul_f32 v[8:9], v[46:47], v[90:91]
	v_pk_fma_f32 v[74:75], v[102:103], v[78:79], v[74:75]
	v_pk_fma_f32 v[102:103], v[46:47], v[78:79], v[6:7]
	v_pk_mul_f32 v[6:7], v[106:107], v[90:91]
	v_pk_fma_f32 v[8:9], v[42:43], v[86:87], v[8:9]
	v_pk_fma_f32 v[6:7], v[46:47], v[86:87], v[6:7]
	v_pk_fma_f32 v[16:17], v[78:79], v[94:95], v[8:9]
	v_pk_mul_f32 v[8:9], v[86:87], v[94:95]
	v_pk_fma_f32 v[106:107], v[42:43], v[78:79], v[6:7]
	v_pk_fma_f32 v[8:9], v[42:43], v[90:91], v[8:9]
	v_pk_mul_f32 v[42:43], v[124:125], s[100:101] op_sel_hi:[1,0]
	v_exp_f32_e32 v42, v42
	v_exp_f32_e32 v43, v43
	v_pk_mul_f32 v[6:7], v[48:49], v[92:93]
	v_pk_fma_f32 v[76:77], v[12:13], v[80:81], v[76:77]
	v_pk_fma_f32 v[6:7], v[44:45], v[88:89], v[6:7]
	v_pk_add_f32 v[42:43], v[42:43], 1.0 op_sel_hi:[1,0]
	v_pk_fma_f32 v[12:13], v[80:81], v[96:97], v[6:7]
	v_pk_mul_f32 v[6:7], v[88:89], v[96:97]
	v_rcp_f32_e32 v42, v42
	v_rcp_f32_e32 v43, v43
	v_pk_fma_f32 v[6:7], v[44:45], v[92:93], v[6:7]
	v_pk_fma_f32 v[8:9], v[78:79], v[98:99], v[8:9]
	v_pk_fma_f32 v[6:7], v[80:81], v[100:101], v[6:7]
	v_pk_mul_f32 v[46:47], v[180:181], v[106:107]
	v_pk_mul_f32 v[44:45], v[122:123], v[6:7]
	v_pk_mul_f32 v[6:7], v[124:125], v[8:9]
	v_pk_mul_f32 v[8:9], v[122:123], s[100:101] op_sel_hi:[1,0]
	v_pk_mul_f32 v[6:7], v[42:43], v[6:7]
	v_exp_f32_e32 v8, v8
	v_exp_f32_e32 v9, v9
	v_pk_mul_f32 v[42:43], v[128:129], s[100:101] op_sel_hi:[1,0]
	v_exp_f32_e32 v42, v42
	v_exp_f32_e32 v43, v43
	v_pk_add_f32 v[8:9], v[8:9], 1.0 op_sel_hi:[1,0]
	v_rcp_f32_e32 v8, v8
	v_rcp_f32_e32 v9, v9
	v_pk_add_f32 v[42:43], v[42:43], 1.0 op_sel_hi:[1,0]
	v_rcp_f32_e32 v42, v42
	v_rcp_f32_e32 v43, v43
	v_pk_mul_f32 v[8:9], v[8:9], v[44:45]
	v_pk_mul_f32 v[44:45], v[126:127], v[12:13]
	v_pk_mul_f32 v[12:13], v[128:129], v[16:17]
	v_mul_f32_e32 v16, 0xbfb8aa3b, v126
	v_pk_mul_f32 v[12:13], v[42:43], v[12:13]
	v_pk_mul_f32 v[42:43], v[180:181], s[100:101] op_sel_hi:[1,0]
	v_exp_f32_e32 v42, v42
	v_exp_f32_e32 v43, v43
	v_mul_f32_e32 v17, 0xbfb8aa3b, v127
	v_exp_f32_e32 v16, v16
	v_pk_add_f32 v[42:43], v[42:43], 1.0 op_sel_hi:[1,0]
	v_rcp_f32_e32 v42, v42
	v_rcp_f32_e32 v43, v43
	v_exp_f32_e32 v17, v17
	v_add_f32_e32 v16, 1.0, v16
	v_pk_mul_f32 v[14:15], v[62:63], v[14:15]
	v_pk_mul_f32 v[42:43], v[42:43], v[46:47]
	v_pk_mul_f32 v[46:47], v[178:179], s[100:101] op_sel_hi:[1,0]
	v_exp_f32_e32 v46, v46
	v_exp_f32_e32 v47, v47
	v_add_f32_e32 v17, 1.0, v17
	v_pk_mul_f32 v[62:63], v[62:63], s[100:101] op_sel_hi:[1,0]
	v_rcp_f32_e32 v16, v16
	v_rcp_f32_e32 v17, v17
	v_pk_add_f32 v[46:47], v[46:47], 1.0 op_sel_hi:[1,0]
	v_exp_f32_e32 v62, v62
	v_exp_f32_e32 v63, v63
	v_rcp_f32_e32 v46, v46
	v_rcp_f32_e32 v47, v47
	v_pk_mul_f32 v[16:17], v[16:17], v[44:45]
	v_pk_mul_f32 v[44:45], v[178:179], v[108:109]
	v_pk_add_f32 v[62:63], v[62:63], 1.0 op_sel_hi:[1,0]
	v_pk_mul_f32 v[44:45], v[46:47], v[44:45]
	v_pk_mul_f32 v[46:47], v[156:157], s[100:101] op_sel_hi:[1,0]
	v_rcp_f32_e32 v62, v62
	v_rcp_f32_e32 v63, v63
	v_exp_f32_e32 v46, v46
	v_exp_f32_e32 v47, v47
	v_pk_mul_f32 v[78:79], v[156:157], v[102:103]
	v_pk_mul_f32 v[14:15], v[62:63], v[14:15]
	v_pk_mul_f32 v[62:63], v[60:61], s[100:101] op_sel_hi:[1,0]
	v_pk_add_f32 v[46:47], v[46:47], 1.0 op_sel_hi:[1,0]
	v_exp_f32_e32 v62, v62
	v_exp_f32_e32 v63, v63
	v_rcp_f32_e32 v46, v46
	v_rcp_f32_e32 v47, v47
	v_pk_add_f32 v[62:63], v[62:63], 1.0 op_sel_hi:[1,0]
	v_rcp_f32_e32 v62, v62
	v_pk_mul_f32 v[46:47], v[46:47], v[78:79]
	v_pk_mul_f32 v[78:79], v[154:155], s[100:101] op_sel_hi:[1,0]
	v_rcp_f32_e32 v63, v63
	v_exp_f32_e32 v78, v78
	v_exp_f32_e32 v79, v79
	v_pk_mul_f32 v[2:3], v[60:61], v[2:3]
	v_pk_mul_f32 v[48:49], v[154:155], v[104:105]
	v_pk_mul_f32 v[60:61], v[62:63], v[2:3]
	v_pk_mul_f32 v[2:3], v[58:59], s[100:101] op_sel_hi:[1,0]
	v_pk_add_f32 v[78:79], v[78:79], 1.0 op_sel_hi:[1,0]
	v_exp_f32_e32 v2, v2
	v_exp_f32_e32 v3, v3
	v_rcp_f32_e32 v78, v78
	v_rcp_f32_e32 v79, v79
	v_pk_add_f32 v[2:3], v[2:3], 1.0 op_sel_hi:[1,0]
	v_rcp_f32_e32 v2, v2
	v_pk_mul_f32 v[48:49], v[78:79], v[48:49]
	v_pk_mul_f32 v[78:79], v[72:73], s[100:101] op_sel_hi:[1,0]
	v_rcp_f32_e32 v3, v3
	v_exp_f32_e32 v78, v78
	v_exp_f32_e32 v79, v79
	v_pk_mul_f32 v[4:5], v[58:59], v[4:5]
	v_pk_mul_f32 v[80:81], v[70:71], v[84:85]
	v_pk_mul_f32 v[58:59], v[2:3], v[4:5]
	v_cvt_pk_bf16_f32 v4, v6, v7
	v_lshrrev_b32_e32 v130, 2, v213
	v_and_b32_e32 v131, 3, v213
	v_lshlrev_b32_e32 v134, 6, v131
	v_lshl_add_u32 v134, v130, 2, v134
	v_sub_u32_e32 v135, v130, v249
	v_lshl_add_u32 v135, v135, 3, v232
	v_sub_u32_e32 v136, v131, v250
	v_lshl_add_u32 v132, v136, 3, v234
	v_mov_b32_e32 v133, v235
	v_lshlrev_b64 v[132:133], 1, v[132:133]
	v_mov_b64_e32 v[6:7], s[46:47]
	v_add_f32_e32 v78, 1.0, v78
	v_add_f32_e32 v79, 1.0, v79
	v_cvt_pk_bf16_f32 v2, v18, v19
	v_cvt_pk_bf16_f32 v5, v8, v9
	v_mad_i64_i32 v[8:9], s[4:5], v135, s92, v[6:7]
	v_lshlrev_b64 v[18:19], 1, v[234:235]
	v_rcp_f32_e32 v78, v78
	v_rcp_f32_e32 v79, v79
	v_cvt_pk_bf16_f32 v3, v20, v21
	v_lshl_add_u64 v[8:9], v[8:9], 0, v[132:133]
	v_mul_f32_e32 v70, 0xbfb8aa3b, v70
	v_mul_f32_e32 v71, 0xbfb8aa3b, v71
	ds_bpermute_b32 v138, v134, v2
	ds_bpermute_b32 v139, v134, v3
	ds_bpermute_b32 v140, v134, v4
	ds_bpermute_b32 v141, v134, v5
	v_mov_b64_e32 v[146:147], v[8:9]
	v_or_b32_e32 v8, 1, v135
	v_exp_f32_e32 v70, v70
	v_exp_f32_e32 v71, v71
	v_mad_i64_i32 v[8:9], s[4:5], v8, s92, v[6:7]
	v_pk_mul_f32 v[72:73], v[72:73], v[82:83]
	v_cvt_pk_bf16_f32 v2, v22, v23
	v_cvt_pk_bf16_f32 v3, v24, v25
	v_cvt_pk_bf16_f32 v4, v12, v13
	v_cvt_pk_bf16_f32 v5, v16, v17
	v_lshl_add_u64 v[8:9], v[8:9], 0, v[132:133]
	v_pk_mul_f32 v[72:73], v[78:79], v[72:73]
	v_mul_f32_e32 v78, 0xbfb8aa3b, v68
	v_mul_f32_e32 v79, 0xbfb8aa3b, v69
	v_pk_mul_f32 v[76:77], v[66:67], v[76:77]
	v_mul_f32_e32 v66, 0xbfb8aa3b, v66
	v_mul_f32_e32 v67, 0xbfb8aa3b, v67
	ds_bpermute_b32 v142, v134, v2
	ds_bpermute_b32 v143, v134, v3
	ds_bpermute_b32 v144, v134, v4
	ds_bpermute_b32 v145, v134, v5
	v_mov_b64_e32 v[148:149], v[8:9]
	s_waitcnt lgkmcnt(4)
	global_store_dwordx4 v[146:147], v[138:141], off
	v_or_b32_e32 v8, 2, v135
	v_exp_f32_e32 v78, v78
	v_exp_f32_e32 v79, v79
	v_exp_f32_e32 v66, v66
	v_exp_f32_e32 v67, v67
	v_mad_i64_i32 v[8:9], s[4:5], v8, s92, v[6:7]
	v_add_f32_e32 v70, 1.0, v70
	v_add_f32_e32 v71, 1.0, v71
	v_cvt_pk_bf16_f32 v2, v26, v27
	v_cvt_pk_bf16_f32 v3, v28, v29
	v_cvt_pk_bf16_f32 v4, v42, v43
	v_cvt_pk_bf16_f32 v5, v44, v45
	v_lshl_add_u64 v[8:9], v[8:9], 0, v[132:133]
	v_rcp_f32_e32 v70, v70
	v_rcp_f32_e32 v71, v71
	v_pk_mul_f32 v[68:69], v[68:69], v[74:75]
	v_mul_f32_e32 v74, 0xbfb8aa3b, v64
	v_mul_f32_e32 v75, 0xbfb8aa3b, v65
	ds_bpermute_b32 v138, v134, v2
	ds_bpermute_b32 v139, v134, v3
	ds_bpermute_b32 v140, v134, v4
	ds_bpermute_b32 v141, v134, v5
	v_mov_b64_e32 v[146:147], v[8:9]
	s_waitcnt lgkmcnt(4)
	global_store_dwordx4 v[148:149], v[142:145], off
	v_or_b32_e32 v8, 3, v135
	v_exp_f32_e32 v74, v74
	v_exp_f32_e32 v75, v75
	v_mad_i64_i32 v[8:9], s[4:5], v8, s92, v[6:7]
	v_add_f32_e32 v78, 1.0, v78
	v_add_f32_e32 v79, 1.0, v79
	v_add_f32_e32 v66, 1.0, v66
	v_add_f32_e32 v67, 1.0, v67
	v_cvt_pk_bf16_f32 v2, v30, v31
	v_cvt_pk_bf16_f32 v3, v32, v33
	v_cvt_pk_bf16_f32 v4, v46, v47
	v_cvt_pk_bf16_f32 v5, v48, v49
	v_lshl_add_u64 v[8:9], v[8:9], 0, v[132:133]
	v_rcp_f32_e32 v78, v78
	v_rcp_f32_e32 v79, v79
	v_rcp_f32_e32 v66, v66
	v_rcp_f32_e32 v67, v67
	ds_bpermute_b32 v142, v134, v2
	ds_bpermute_b32 v143, v134, v3
	ds_bpermute_b32 v144, v134, v4
	ds_bpermute_b32 v145, v134, v5
	v_mov_b64_e32 v[148:149], v[8:9]
	s_waitcnt lgkmcnt(4)
	global_store_dwordx4 v[146:147], v[138:141], off
	v_or_b32_e32 v8, 4, v135
	v_pk_mul_f32 v[70:71], v[70:71], v[80:81]
	v_mad_i64_i32 v[8:9], s[4:5], v8, s92, v[6:7]
	v_add_f32_e32 v74, 1.0, v74
	v_add_f32_e32 v75, 1.0, v75
	v_cvt_pk_bf16_f32 v2, v34, v35
	v_cvt_pk_bf16_f32 v3, v36, v37
	v_cvt_pk_bf16_f32 v4, v72, v73
	v_cvt_pk_bf16_f32 v5, v70, v71
	v_lshl_add_u64 v[8:9], v[8:9], 0, v[132:133]
	v_rcp_f32_e32 v74, v74
	v_rcp_f32_e32 v75, v75
	ds_bpermute_b32 v138, v134, v2
	ds_bpermute_b32 v139, v134, v3
	ds_bpermute_b32 v140, v134, v4
	ds_bpermute_b32 v141, v134, v5
	v_mov_b64_e32 v[146:147], v[8:9]
	s_waitcnt lgkmcnt(4)
	global_store_dwordx4 v[148:149], v[142:145], off
	v_or_b32_e32 v8, 5, v135
	v_pk_mul_f32 v[68:69], v[78:79], v[68:69]
	v_pk_mul_f32 v[66:67], v[66:67], v[76:77]
	v_mad_i64_i32 v[8:9], s[4:5], v8, s92, v[6:7]
	v_cvt_pk_bf16_f32 v2, v38, v39
	v_cvt_pk_bf16_f32 v3, v40, v41
	v_cvt_pk_bf16_f32 v4, v68, v69
	v_cvt_pk_bf16_f32 v5, v66, v67
	v_lshl_add_u64 v[8:9], v[8:9], 0, v[132:133]
	v_pk_mul_f32 v[10:11], v[64:65], v[10:11]
	ds_bpermute_b32 v142, v134, v2
	ds_bpermute_b32 v143, v134, v3
	ds_bpermute_b32 v144, v134, v4
	ds_bpermute_b32 v145, v134, v5
	v_mov_b64_e32 v[148:149], v[8:9]
	s_waitcnt lgkmcnt(4)
	global_store_dwordx4 v[146:147], v[138:141], off
	v_or_b32_e32 v8, 6, v135
	v_pk_mul_f32 v[10:11], v[74:75], v[10:11]
	v_mad_i64_i32 v[8:9], s[4:5], v8, s92, v[6:7]
	v_cvt_pk_bf16_f32 v2, v50, v51
	v_cvt_pk_bf16_f32 v3, v52, v53
	v_cvt_pk_bf16_f32 v4, v10, v11
	v_cvt_pk_bf16_f32 v5, v14, v15
	v_lshl_add_u64 v[8:9], v[8:9], 0, v[132:133]
	ds_bpermute_b32 v138, v134, v2
	ds_bpermute_b32 v139, v134, v3
	ds_bpermute_b32 v140, v134, v4
	ds_bpermute_b32 v141, v134, v5
	v_mov_b64_e32 v[146:147], v[8:9]
	s_waitcnt lgkmcnt(4)
	global_store_dwordx4 v[148:149], v[142:145], off
	v_or_b32_e32 v8, 7, v135
	v_mad_i64_i32 v[6:7], s[4:5], v8, s92, v[6:7]
	v_cvt_pk_bf16_f32 v2, v54, v55
	v_cvt_pk_bf16_f32 v3, v56, v57
	v_cvt_pk_bf16_f32 v4, v60, v61
	v_cvt_pk_bf16_f32 v5, v58, v59
	v_lshl_add_u64 v[6:7], v[6:7], 0, v[132:133]
	ds_bpermute_b32 v142, v134, v2
	ds_bpermute_b32 v143, v134, v3
	ds_bpermute_b32 v144, v134, v4
	ds_bpermute_b32 v145, v134, v5
	v_mov_b64_e32 v[148:149], v[6:7]
	s_waitcnt lgkmcnt(4)
	global_store_dwordx4 v[146:147], v[138:141], off
	s_andn2_b64 vcc, exec, s[40:41]
	s_waitcnt lgkmcnt(0)
	global_store_dwordx4 v[148:149], v[142:145], off
	s_cbranch_vccnz .LBB0_386
	s_andn2_b64 vcc, exec, s[24:25]
	s_cbranch_vccnz .LBB0_385
	s_barrier
	s_branch .LBB0_385
